# attncsel + G3 K-loop shifted by 4 bytes (8-byte aligned loop head), compensating nop after the loop
# baseline (speedup 1.0000x reference)
; template <class Epi, class Sched, bool ALIGN_EPI = false, bool SP2 = false>
; __device__ __forceinline__ void gemm_phase(PG8_LAS unsigned char* lds, const Gemm g, const Sched& S, const Epi& E) {
;     ...
; #pragma unroll
;         for (int a = 0; a < 2; ++a)
; #pragma unroll
;             for (int b = 0; b < 2; ++b)
; #pragma unroll
;                 for (int m = 0; m < 4; ++m)
; #pragma unroll
;                     for (int n = 0; n < 2; ++n) acc[a][b][m][n] = (f32x4){0.f, 0.f, 0.f, 0.f};
.Lzero_g3:
	v_mov_b32_e32 v0, 0
	v_mov_b32_e32 v1, v0
	v_mov_b32_e32 v2, v0
	v_mov_b32_e32 v3, v0
	v_mov_b32_e32 v4, v0
	v_mov_b32_e32 v5, v0
	v_mov_b32_e32 v6, v0
	v_mov_b32_e32 v7, v0
	v_mov_b32_e32 v16, v0
	v_mov_b32_e32 v17, v0
	v_mov_b32_e32 v18, v0
	v_mov_b32_e32 v19, v0
	v_mov_b32_e32 v20, v0
	v_mov_b32_e32 v21, v0
	v_mov_b32_e32 v22, v0
	v_mov_b32_e32 v23, v0
	v_mov_b32_e32 v32, v0
	v_mov_b32_e32 v33, v0
	v_mov_b32_e32 v34, v0
	v_mov_b32_e32 v35, v0
	v_mov_b32_e32 v36, v0
	v_mov_b32_e32 v37, v0
	v_mov_b32_e32 v38, v0
	v_mov_b32_e32 v39, v0
	v_mov_b32_e32 v48, v0
	v_mov_b32_e32 v49, v0
	v_mov_b32_e32 v50, v0
	v_mov_b32_e32 v51, v0
	v_mov_b32_e32 v52, v0
	v_mov_b32_e32 v53, v0
	v_mov_b32_e32 v54, v0
	v_mov_b32_e32 v55, v0
	v_mov_b32_e32 v8, v0
	v_mov_b32_e32 v9, v0
	v_mov_b32_e32 v10, v0
	v_mov_b32_e32 v11, v0
	v_mov_b32_e32 v12, v0
	v_mov_b32_e32 v13, v0
	v_mov_b32_e32 v14, v0
	v_mov_b32_e32 v15, v0
	v_mov_b32_e32 v24, v0
	v_mov_b32_e32 v25, v0
	v_mov_b32_e32 v26, v0
	v_mov_b32_e32 v27, v0
	v_mov_b32_e32 v28, v0
	v_mov_b32_e32 v29, v0
	v_mov_b32_e32 v30, v0
	v_mov_b32_e32 v31, v0
	v_mov_b32_e32 v40, v0
	v_mov_b32_e32 v41, v0
	v_mov_b32_e32 v42, v0
	v_mov_b32_e32 v43, v0
	v_mov_b32_e32 v44, v0
	v_mov_b32_e32 v45, v0
	v_mov_b32_e32 v46, v0
	v_mov_b32_e32 v47, v0
	v_mov_b32_e32 v56, v0
	v_mov_b32_e32 v57, v0
	v_mov_b32_e32 v58, v0
	v_mov_b32_e32 v59, v0
	v_mov_b32_e32 v60, v0
	v_mov_b32_e32 v61, v0
	v_mov_b32_e32 v62, v0
	v_mov_b32_e32 v63, v0
	v_mov_b32_e32 v64, v0
	v_mov_b32_e32 v65, v0
	v_mov_b32_e32 v66, v0
	v_mov_b32_e32 v67, v0
	v_mov_b32_e32 v68, v0
	v_mov_b32_e32 v69, v0
	v_mov_b32_e32 v70, v0
	v_mov_b32_e32 v71, v0
	v_mov_b32_e32 v80, v0
	v_mov_b32_e32 v81, v0
	v_mov_b32_e32 v82, v0
	v_mov_b32_e32 v83, v0
	v_mov_b32_e32 v84, v0
	v_mov_b32_e32 v85, v0
	v_mov_b32_e32 v86, v0
	v_mov_b32_e32 v87, v0
	v_mov_b32_e32 v96, v0
	v_mov_b32_e32 v97, v0
	v_mov_b32_e32 v98, v0
	v_mov_b32_e32 v99, v0
	v_mov_b32_e32 v100, v0
	v_mov_b32_e32 v101, v0
	v_mov_b32_e32 v102, v0
	v_mov_b32_e32 v103, v0
	v_mov_b32_e32 v112, v0
	v_mov_b32_e32 v113, v0
	v_mov_b32_e32 v114, v0
	v_mov_b32_e32 v115, v0
	v_mov_b32_e32 v116, v0
	v_mov_b32_e32 v117, v0
	v_mov_b32_e32 v118, v0
	v_mov_b32_e32 v119, v0
	v_mov_b32_e32 v72, v0
	v_mov_b32_e32 v73, v0
	v_mov_b32_e32 v74, v0
	v_mov_b32_e32 v75, v0
	v_mov_b32_e32 v76, v0
	v_mov_b32_e32 v77, v0
	v_mov_b32_e32 v78, v0
	v_mov_b32_e32 v79, v0
	v_mov_b32_e32 v88, v0
	v_mov_b32_e32 v89, v0
	v_mov_b32_e32 v90, v0
	v_mov_b32_e32 v91, v0
	v_mov_b32_e32 v92, v0
	v_mov_b32_e32 v93, v0
	v_mov_b32_e32 v94, v0
	v_mov_b32_e32 v95, v0
	v_mov_b32_e32 v104, v0
	v_mov_b32_e32 v105, v0
	v_mov_b32_e32 v106, v0
	v_mov_b32_e32 v107, v0
	v_mov_b32_e32 v108, v0
	v_mov_b32_e32 v109, v0
	v_mov_b32_e32 v110, v0
	v_mov_b32_e32 v111, v0
	v_mov_b32_e32 v120, v0
	v_mov_b32_e32 v121, v0
	v_mov_b32_e32 v122, v0
	v_mov_b32_e32 v123, v0
	v_mov_b32_e32 v124, v0
	v_mov_b32_e32 v125, v0
	v_mov_b32_e32 v126, v0
	v_mov_b32_e32 v127, v0
	s_nop 0

; #define PG8_STAGE(bufoff, gbase, voff) do { _Pragma("unroll") for (int _i = 0; _i < 2; ++_i) \
;         __builtin_amdgcn_global_load_lds((const unsigned*)((const char*)(gbase) + (voff)[_i]), (PG8_LAS unsigned*)(lds + (bufoff) + ldsw + _i * 8192), 16, 0, 0); } while (0)
; #define PG8_LDA(dst, b, h) do { _Pragma("unroll") for (int m = 0; m < 4; ++m) _Pragma("unroll") for (int k = 0; k < 2; ++k) dst[m][k] = *(const PG8_LAS bf16x8*)(lds + PG8_SA(b, h) + aoff + m * 2048 + k * 1024); } while (0)
; #define PG8_LDB(dst, b, h) do { _Pragma("unroll") for (int n = 0; n < 2; ++n) _Pragma("unroll") for (int k = 0; k < 2; ++k) dst[n][k] = *(const PG8_LAS bf16x8*)(lds + PG8_SB(b, h) + boff + n * 2048 + k * 1024); } while (0)
; #define PG8_MMA(ai, bj, At, Bt) do { __builtin_amdgcn_s_setprio(1); _Pragma("unroll") for (int m = 0; m < 4; ++m) _Pragma("unroll") for (int n = 0; n < 2; ++n) _Pragma("unroll") for (int k = 0; k < 2; ++k) \
;         acc[ai][bj][m][n] = __builtin_amdgcn_mfma_f32_16x16x32_bf16(Bt[n][k], At[m][k], acc[ai][bj][m][n], 0, 0, 0); __builtin_amdgcn_s_setprio(0); } while (0)
; #define PG8_WAIT_V(n) asm volatile("s_waitcnt vmcnt(" #n ")" ::: "memory")
; #define PG8_WAIT_L(n) asm volatile("s_waitcnt lgkmcnt(" #n ")" ::: "memory")
; #define PG8_BAR __builtin_amdgcn_s_barrier()
; #define PG8_SCHED __builtin_amdgcn_sched_barrier(0)
; template <class Epi, class Sched, bool ALIGN_EPI = false, bool SP2 = false>
; __device__ __forceinline__ void gemm_phase(PG8_LAS unsigned char* lds, const Gemm g, const Sched& S, const Epi& E) {
;     ...
;             PG8_LDB(B0, 1, 0); PG8_LDB(B1, 1, 1); PG8_SCHED; PG8_LDA(At, 1, 0); PG8_STAGE(PG8_SA(0, 1), a2 + hstep, voffA);
;             PG8_WAIT_V(8); PG8_WAIT_L(0); PG8_BAR; PG8_MMA(0, 0, At, B0); PG8_MMA(0, 1, At, B1); PG8_BAR; PG8_SCHED;
.Lmid_g3:
	s_add_i32 s5, 0, 0x18000
	v_add_u32_e32 v143, s5, v157
	s_add_i32 s8, 0, 0x1c000
	ds_read_b128 v[162:165], v143
	ds_read_b128 v[166:169], v143 offset:1024
	ds_read_b128 v[170:173], v143 offset:2048
	ds_read_b128 v[174:177], v143 offset:3072
	v_add_u32_e32 v143, s8, v157
	ds_read_b128 v[178:181], v143
	ds_read_b128 v[182:185], v143 offset:1024
	ds_read_b128 v[186:189], v143 offset:2048
	ds_read_b128 v[190:193], v143 offset:3072
	s_add_u32 s20, s62, 0x40000
	s_addc_u32 s21, s63, 0
	s_mov_b32 m0, s67
	v_lshl_add_u64 v[246:247], s[20:21], 0, v[134:135]
	ds_read_b128 v[200:203], v161 offset:32768
	ds_read_b128 v[204:207], v161 offset:33792
	ds_read_b128 v[208:211], v161 offset:34816
	ds_read_b128 v[212:215], v161 offset:35840
	ds_read_b128 v[216:219], v161 offset:36864
	ds_read_b128 v[220:223], v161 offset:37888
	ds_read_b128 v[224:227], v161 offset:38912
	ds_read_b128 v[228:231], v161 offset:39936
	global_load_lds_dwordx4 v[246:247], off
	v_lshl_add_u64 v[246:247], s[20:21], 0, v[130:131]
	s_mov_b32 m0, s68
	s_nop 0
	global_load_lds_dwordx4 v[246:247], off
	s_waitcnt vmcnt(8)
	s_waitcnt lgkmcnt(0)
	s_barrier
	s_setprio 1
	s_waitcnt lgkmcnt(0)
	v_mfma_f32_16x16x32_bf16 v[124:127], v[162:165], v[200:203], v[124:127]
	v_mfma_f32_16x16x32_bf16 v[120:123], v[170:173], v[200:203], v[120:123]
	v_mfma_f32_16x16x32_bf16 v[108:111], v[162:165], v[208:211], v[108:111]
	v_mfma_f32_16x16x32_bf16 v[104:107], v[170:173], v[208:211], v[104:107]
	v_mfma_f32_16x16x32_bf16 v[92:95], v[162:165], v[216:219], v[92:95]
	v_mfma_f32_16x16x32_bf16 v[88:91], v[170:173], v[216:219], v[88:91]
	v_mfma_f32_16x16x32_bf16 v[76:79], v[162:165], v[224:227], v[76:79]
	v_mfma_f32_16x16x32_bf16 v[72:75], v[170:173], v[224:227], v[72:75]
	v_mfma_f32_16x16x32_bf16 v[124:127], v[166:169], v[204:207], v[124:127]
	v_mfma_f32_16x16x32_bf16 v[120:123], v[174:177], v[204:207], v[120:123]
	v_mfma_f32_16x16x32_bf16 v[108:111], v[166:169], v[212:215], v[108:111]
	v_mfma_f32_16x16x32_bf16 v[104:107], v[174:177], v[212:215], v[104:107]
	v_mfma_f32_16x16x32_bf16 v[92:95], v[166:169], v[220:223], v[92:95]
	v_mfma_f32_16x16x32_bf16 v[88:91], v[174:177], v[220:223], v[88:91]
	v_mfma_f32_16x16x32_bf16 v[76:79], v[166:169], v[228:231], v[76:79]
	v_mfma_f32_16x16x32_bf16 v[72:75], v[174:177], v[228:231], v[72:75]
	s_setprio 0
	s_setprio 1
	v_mfma_f32_16x16x32_bf16 v[116:119], v[178:181], v[200:203], v[116:119]
	v_mfma_f32_16x16x32_bf16 v[112:115], v[186:189], v[200:203], v[112:115]
	v_mfma_f32_16x16x32_bf16 v[100:103], v[178:181], v[208:211], v[100:103]
	v_mfma_f32_16x16x32_bf16 v[96:99], v[186:189], v[208:211], v[96:99]
	v_mfma_f32_16x16x32_bf16 v[84:87], v[178:181], v[216:219], v[84:87]
	v_mfma_f32_16x16x32_bf16 v[80:83], v[186:189], v[216:219], v[80:83]
	v_mfma_f32_16x16x32_bf16 v[68:71], v[178:181], v[224:227], v[68:71]
	v_mfma_f32_16x16x32_bf16 v[64:67], v[186:189], v[224:227], v[64:67]
	v_mfma_f32_16x16x32_bf16 v[116:119], v[182:185], v[204:207], v[116:119]
	v_mfma_f32_16x16x32_bf16 v[112:115], v[190:193], v[204:207], v[112:115]
	v_mfma_f32_16x16x32_bf16 v[100:103], v[182:185], v[212:215], v[100:103]
	v_mfma_f32_16x16x32_bf16 v[96:99], v[190:193], v[212:215], v[96:99]
	v_mfma_f32_16x16x32_bf16 v[84:87], v[182:185], v[220:223], v[84:87]
	v_mfma_f32_16x16x32_bf16 v[80:83], v[190:193], v[220:223], v[80:83]
	v_mfma_f32_16x16x32_bf16 v[68:71], v[182:185], v[228:231], v[68:71]
	v_mfma_f32_16x16x32_bf16 v[64:67], v[190:193], v[228:231], v[64:67]
	s_setprio 0
	s_barrier
; #define PG8_STAGE(bufoff, gbase, voff) do { _Pragma("unroll") for (int _i = 0; _i < 2; ++_i) \
;         __builtin_amdgcn_global_load_lds((const unsigned*)((const char*)(gbase) + (voff)[_i]), (PG8_LAS unsigned*)(lds + (bufoff) + ldsw + _i * 8192), 16, 0, 0); } while (0)
; #define PG8_LDA(dst, b, h) do { _Pragma("unroll") for (int m = 0; m < 4; ++m) _Pragma("unroll") for (int k = 0; k < 2; ++k) dst[m][k] = *(const PG8_LAS bf16x8*)(lds + PG8_SA(b, h) + aoff + m * 2048 + k * 1024); } while (0)
; #define PG8_MMA(ai, bj, At, Bt) do { __builtin_amdgcn_s_setprio(1); _Pragma("unroll") for (int m = 0; m < 4; ++m) _Pragma("unroll") for (int n = 0; n < 2; ++n) _Pragma("unroll") for (int k = 0; k < 2; ++k) \
;         acc[ai][bj][m][n] = __builtin_amdgcn_mfma_f32_16x16x32_bf16(Bt[n][k], At[m][k], acc[ai][bj][m][n], 0, 0, 0); __builtin_amdgcn_s_setprio(0); } while (0)
; #define PG8_WAIT_V(n) asm volatile("s_waitcnt vmcnt(" #n ")" ::: "memory")
; #define PG8_WAIT_L(n) asm volatile("s_waitcnt lgkmcnt(" #n ")" ::: "memory")
; #define PG8_BAR __builtin_amdgcn_s_barrier()
; #define PG8_SCHED __builtin_amdgcn_sched_barrier(0)
; template <class Epi, class Sched, bool ALIGN_EPI = false, bool SP2 = false>
; __device__ __forceinline__ void gemm_phase(PG8_LAS unsigned char* lds, const Gemm g, const Sched& S, const Epi& E) {
;     ...
;         for (int t = 0; t < nt; t += 2) {
;     ...
;             PG8_LDA(At, 1, 1); PG8_STAGE(PG8_SB(1, 0), b3, voffB); PG8_STAGE(PG8_SB(1, 1), b3 + hstep, voffB); PG8_STAGE(PG8_SA(1, 0), a3, voffA);
;             PG8_WAIT_V(8); PG8_WAIT_L(0); PG8_BAR; PG8_MMA(1, 0, At, B0); PG8_MMA(1, 1, At, B1); PG8_BAR; PG8_SCHED;
	s_add_i32 s5, s5, s64
	v_lshl_add_u64 v[194:195], v[194:195], 0, s[22:23]
	s_mov_b32 m0, s5
	ds_read_b128 v[200:203], v161 offset:49152
	ds_read_b128 v[204:207], v161 offset:50176
	ds_read_b128 v[208:211], v161 offset:51200
	ds_read_b128 v[212:215], v161 offset:52224
	ds_read_b128 v[216:219], v161 offset:53248
	ds_read_b128 v[220:223], v161 offset:54272
	ds_read_b128 v[224:227], v161 offset:55296
	ds_read_b128 v[228:231], v161 offset:56320
	global_load_lds_dwordx4 v[194:195], off
	s_add_i32 m0, s5, 0x2000
	s_add_u32 s20, s60, 0x40080
	v_lshl_add_u64 v[194:195], v[240:241], 0, s[22:23]
	s_addc_u32 s21, s61, 0
	s_add_i32 s5, s8, s64
	global_load_lds_dwordx4 v[194:195], off
	v_lshl_add_u64 v[194:195], s[20:21], 0, v[132:133]
	s_mov_b32 m0, s5
	s_nop 0
	global_load_lds_dwordx4 v[194:195], off
	v_lshl_add_u64 v[194:195], s[20:21], 0, v[128:129]
	s_add_i32 m0, s5, 0x2000
	s_nop 0
	global_load_lds_dwordx4 v[194:195], off
	v_lshl_add_u64 v[194:195], v[242:243], 0, s[22:23]
	s_mov_b32 m0, s69
	s_nop 0
	global_load_lds_dwordx4 v[194:195], off
	v_lshl_add_u64 v[194:195], v[244:245], 0, s[22:23]
	s_mov_b32 m0, s70
	s_nop 0
	global_load_lds_dwordx4 v[194:195], off
	s_waitcnt vmcnt(8)
	s_waitcnt lgkmcnt(0)
	s_barrier
	s_setprio 1
	s_waitcnt lgkmcnt(0)
	v_mfma_f32_16x16x32_bf16 v[60:63], v[162:165], v[200:203], v[60:63]
	v_mfma_f32_16x16x32_bf16 v[56:59], v[170:173], v[200:203], v[56:59]
	v_mfma_f32_16x16x32_bf16 v[44:47], v[162:165], v[208:211], v[44:47]
	v_mfma_f32_16x16x32_bf16 v[40:43], v[170:173], v[208:211], v[40:43]
	v_mfma_f32_16x16x32_bf16 v[28:31], v[162:165], v[216:219], v[28:31]
	v_mfma_f32_16x16x32_bf16 v[24:27], v[170:173], v[216:219], v[24:27]
	v_mfma_f32_16x16x32_bf16 v[12:15], v[162:165], v[224:227], v[12:15]
	v_mfma_f32_16x16x32_bf16 v[8:11], v[170:173], v[224:227], v[8:11]
	v_mfma_f32_16x16x32_bf16 v[60:63], v[166:169], v[204:207], v[60:63]
	v_mfma_f32_16x16x32_bf16 v[56:59], v[174:177], v[204:207], v[56:59]
	v_mfma_f32_16x16x32_bf16 v[44:47], v[166:169], v[212:215], v[44:47]
	v_mfma_f32_16x16x32_bf16 v[40:43], v[174:177], v[212:215], v[40:43]
	v_mfma_f32_16x16x32_bf16 v[28:31], v[166:169], v[220:223], v[28:31]
	v_mfma_f32_16x16x32_bf16 v[24:27], v[174:177], v[220:223], v[24:27]
	v_mfma_f32_16x16x32_bf16 v[12:15], v[166:169], v[228:231], v[12:15]
	v_mfma_f32_16x16x32_bf16 v[8:11], v[174:177], v[228:231], v[8:11]
	s_setprio 0
	s_setprio 1
	v_mfma_f32_16x16x32_bf16 v[52:55], v[178:181], v[200:203], v[52:55]
	v_mfma_f32_16x16x32_bf16 v[48:51], v[186:189], v[200:203], v[48:51]
	v_mfma_f32_16x16x32_bf16 v[36:39], v[178:181], v[208:211], v[36:39]
	v_mfma_f32_16x16x32_bf16 v[32:35], v[186:189], v[208:211], v[32:35]
	v_mfma_f32_16x16x32_bf16 v[20:23], v[178:181], v[216:219], v[20:23]
	v_mfma_f32_16x16x32_bf16 v[16:19], v[186:189], v[216:219], v[16:19]
	v_mfma_f32_16x16x32_bf16 v[4:7], v[178:181], v[224:227], v[4:7]
	v_mfma_f32_16x16x32_bf16 v[0:3], v[186:189], v[224:227], v[0:3]
	v_mfma_f32_16x16x32_bf16 v[52:55], v[182:185], v[204:207], v[52:55]
	v_mfma_f32_16x16x32_bf16 v[48:51], v[190:193], v[204:207], v[48:51]
	v_mfma_f32_16x16x32_bf16 v[36:39], v[182:185], v[212:215], v[36:39]
	v_mfma_f32_16x16x32_bf16 v[32:35], v[190:193], v[212:215], v[32:35]
	v_mfma_f32_16x16x32_bf16 v[20:23], v[182:185], v[220:223], v[20:23]
	v_mfma_f32_16x16x32_bf16 v[16:19], v[190:193], v[220:223], v[16:19]
	v_mfma_f32_16x16x32_bf16 v[4:7], v[182:185], v[228:231], v[4:7]
	v_mfma_f32_16x16x32_bf16 v[0:3], v[190:193], v[228:231], v[0:3]
	s_setprio 0
	s_barrier
	s_add_i32 s72, s72, 2
	s_add_u32 s51, s51, 0x100
	s_addc_u32 s53, s53, 0
	s_add_u32 s58, s58, 0x100
	s_addc_u32 s59, s59, 0
	s_cmp_gt_u32 s72, 13
	s_cbranch_scc0 .LBB0_152
	s_nop 0
	s_and_b64 vcc, exec, s[48:49]
	s_cbranch_vccz .LBB0_155
	s_barrier
